# skip cg sync + final barrier; FF1 epilogue loads hoisted; 1us-per-row-group start stagger in in-proj and FFN-up GEMM phases so tile epilogue stores of an XCD do not coincide
# speedup vs baseline: 1.0088x; 1.0088x over previous
; __device__ __forceinline__ unsigned xb_add(unsigned* p, unsigned v) { return __hip_atomic_fetch_add(p, v, RLX_AGENT); }
; __device__ __forceinline__ unsigned xb_xcc_id() { return (unsigned)__builtin_amdgcn_s_getreg((3 << 11) | 20) & 0xFu; }
; __global__ void __launch_bounds__(512, 2) hybrid_fwd(Args A0) {
;     ...
;     { int l0; asm volatile("v_mbcnt_lo_u32_b32 %0, -1, 0\n\tv_mbcnt_hi_u32_b32 %0, -1, %0" : "=v"(l0));
;       if (wave == 0 && l0 == 0) { const unsigned x0 = xb_xcc_id(); bst[0] = 0u; bst[1] = 0u; bst[3] = x0; bst[2] = xb_add(&((unsigned*)ws)[XB_XCNT(x0)], 1u); } }
;     grid.sync();
.LBB0_4:
	s_or_b64 exec, exec, s[4:5]
	v_lshrrev_b32_e32 v2, 20, v0
	v_lshrrev_b32_e32 v0, 10, v0
	v_or_b32_e32 v0, v0, v2
	s_movk_i32 s0, 0x3ff
	v_and_or_b32 v0, v0, s0, v1
	v_cmp_eq_u32_e32 vcc, 0, v0
	s_waitcnt lgkmcnt(0)
	s_barrier
	s_and_saveexec_b64 s[4:5], vcc
	s_branch .LBB0_14

; #define PHASE_BEGIN(id) if (((PHMASK >> (id)) & 1u) && ph >= ph_lo && ph < ph_hi) { const Args A = load_args(); int lane; asm volatile("v_mbcnt_lo_u32_b32 %0, -1, 0\n\tv_mbcnt_hi_u32_b32 %0, -1, %0" : "=v"(lane)); const int tid = wave * 64 + lane, gw = bid * 8 + wave; (void)tid; LAS float* scr = (LAS float*)(lds + wave * 16384); (void)lane; (void)gw; (void)scr;
;     __device__ bool next(int i, Unit& u) const {
;         const long L = (long)i * G + c; if (L >= nwg) return false;
;         int wgid = (int)L; { const int q = nwg / NXCD, r = nwg % NXCD, xcd = wgid % NXCD, off = wgid / NXCD; wgid = (xcd < r ? xcd * (q + 1) : r * (q + 1) + (xcd - r) * q) + off; }
;         const int nig = wgm * nN, gid = wgid / nig, fm = gid * wgm, gsz = (nM - fm) < wgm ? (nM - fm) : wgm;
;         u.pm = fm + ((wgid % nig) % gsz); u.pn = (wgid % nig) / gsz; u.offA = u.pm * sA; u.offB = u.pn * sB; u.chain = 0; u.aux = 0; return true;
; __global__ void __launch_bounds__(512, 2) hybrid_fwd(Args A0) {
;     ...
;     PHASE_BEGIN(1)
;         const Gemm g{(const bf16_t*)(ws + WS_H), (const bf16_t*)(ws + WS_WTIN), DM, DM, DM};
;         pg8::StaticOrder S; S.init(T, NPROJ_PAD, DM, DM, G, bid);
;         Epi<M_INPROJ> E{&A, 0};
;         pg8::gemm_phase<Epi<M_INPROJ>, pg8::StaticOrder, true>(lds, g, S, E, wave);
.LBB0_319:
	s_bfe_u32 s98, s2, 0x30003
	s_mul_i32 s98, s98, 100
	s_and_b32 s99, s2, 7
	s_mul_i32 s99, s99, 0
	s_add_u32 s98, s98, s99
	s_memrealtime s[100:101]
	s_waitcnt lgkmcnt(0)
	s_mov_b32 s99, s100
.Lstag_p1:
	s_memrealtime s[100:101]
	s_waitcnt lgkmcnt(0)
	s_sub_u32 s100, s100, s99
	s_cmp_lt_u32 s100, s98
	s_cbranch_scc1 .Lstag_p1
	s_cmp_lt_i32 s42, 2
	s_cselect_b64 s[84:85], -1, 0
	s_and_b64 s[0:1], s[84:85], s[4:5]
	s_andn2_b64 vcc, exec, s[0:1]
	s_cbranch_vccnz .LBB0_1014
	v_readlane_b32 s18, v255, 0
	v_readlane_b32 s19, v255, 1
	s_cmpk_lt_i32 s2, 0xf40
	v_mbcnt_lo_u32_b32 v0, -1, 0
	v_mbcnt_hi_u32_b32 v0, -1, v0
	s_cselect_b64 s[12:13], -1, 0
	s_cmpk_gt_i32 s2, 0xf3f
	v_mbcnt_lo_u32_b32 v0, -1, 0
	v_mbcnt_hi_u32_b32 v0, -1, v0
	s_cbranch_scc1 .LBB0_322
	s_ashr_i32 s0, s2, 31
	s_lshr_b32 s0, s0, 29
	s_add_i32 s0, s2, s0
	s_ashr_i32 s1, s0, 3
	s_and_b32 s0, s0, -8
	s_sub_i32 s0, s2, s0
	s_cmp_lt_i32 s0, 0
	s_movk_i32 s3, 0x1e9
	s_cselect_b32 s3, s3, 0x1e8
	s_mul_i32 s0, s0, s3
	s_add_i32 s0, s0, s1
	s_mul_hi_i32 s1, s0, 0x4325c53f
	s_lshr_b32 s3, s1, 31
	s_ashr_i32 s1, s1, 7
	s_add_i32 s1, s1, s3
	s_lshl_b32 s3, s1, 3
	s_mulk_i32 s1, 0x1e8
	s_sub_i32 s1, s0, s1
	s_sext_i32_i16 s0, s1
	s_bfe_u32 s0, s0, 0x3001c
	s_add_i32 s4, s1, s0
	s_sext_i32_i16 s5, s4
	s_and_b32 s4, s4, 0xfff8
	s_sub_i32 s1, s1, s4
	s_sext_i32_i16 s1, s1
	s_lshr_b32 s0, s5, 3
	s_add_i32 s6, s3, s1
	s_ashr_i32 s7, s6, 31
	s_bfe_i64 s[0:1], s[0:1], 0x100000
	s_ashr_i32 s76, s5, 3
	s_lshl_b64 s[4:5], s[6:7], 20
	s_lshl_b64 s[8:9], s[0:1], 20
	s_andn2_b64 vcc, exec, s[12:13]
	s_cbranch_vccz .LBB0_323
	s_branch .LBB0_1014

; #define PHASE_BEGIN(id) if (((PHMASK >> (id)) & 1u) && ph >= ph_lo && ph < ph_hi) { const Args A = load_args(); int lane; asm volatile("v_mbcnt_lo_u32_b32 %0, -1, 0\n\tv_mbcnt_hi_u32_b32 %0, -1, %0" : "=v"(lane)); const int tid = wave * 64 + lane, gw = bid * 8 + wave; (void)tid; LAS float* scr = (LAS float*)(lds + wave * 16384); (void)lane; (void)gw; (void)scr;
;     __device__ bool next(int i, Unit& u) const {
;         const long L = (long)i * G + c; if (L >= nwg) return false;
;         int wgid = (int)L; { const int q = nwg / NXCD, r = nwg % NXCD, xcd = wgid % NXCD, off = wgid / NXCD; wgid = (xcd < r ? xcd * (q + 1) : r * (q + 1) + (xcd - r) * q) + off; }
;         const int nig = wgm * nN, gid = wgid / nig, fm = gid * wgm, gsz = (nM - fm) < wgm ? (nM - fm) : wgm;
;         u.pm = fm + ((wgid % nig) % gsz); u.pn = (wgid % nig) / gsz; u.offA = u.pm * sA; u.offB = u.pn * sB; u.chain = 0; u.aux = 0; return true;
; __global__ void __launch_bounds__(512, 2) hybrid_fwd(Args A0) {
;     ...
;     PHASE_BEGIN(14)
;         const Gemm g{(const bf16_t*)(ws + WS_H2), (const bf16_t*)(ws + WS_WF1), DM, DM, DM};
;         pg8::StaticOrder S; S.init(T, DFF, DM, DM, G, bid); Epi<M_FF1> E{&A, 0};
;         pg8::gemm_phase<Epi<M_FF1>, pg8::StaticOrder, true>(lds, g, S, E, wave);
.Lstag_p14:
	s_memrealtime s[100:101]
	s_waitcnt lgkmcnt(0)
	s_sub_u32 s100, s100, s99
	s_cmp_lt_u32 s100, s98
	s_cbranch_scc1 .Lstag_p14
	s_cmp_lt_i32 s42, 17
	s_cselect_b64 s[12:13], -1, 0
	s_and_b64 s[0:1], s[12:13], s[4:5]
	s_andn2_b64 vcc, exec, s[0:1]
	s_cbranch_vccnz .LBB0_5623
	v_readlane_b32 s4, v255, 0
	v_readlane_b32 s5, v255, 1
	s_waitcnt vmcnt(0)
	v_mbcnt_lo_u32_b32 v0, -1, 0
	v_mbcnt_hi_u32_b32 v0, -1, v0
	s_cmpk_gt_i32 s2, 0x7ff
	v_mbcnt_lo_u32_b32 v0, -1, 0
	v_mbcnt_hi_u32_b32 v0, -1, v0
	s_cbranch_scc1 .LBB0_5623
	s_ashr_i32 s0, s2, 31
	s_lshr_b32 s1, s0, 29
	s_add_i32 s1, s2, s1
	s_and_b32 s3, s1, -8
	s_sub_i32 s3, s2, s3
	s_cmp_gt_i32 s3, -1
	s_cbranch_scc0 .LBB0_5602
	s_waitcnt lgkmcnt(0)
	s_lshl_b32 s8, s3, 8
	s_load_dwordx2 s[4:5], s[4:5], 0x88
	s_cbranch_execz .LBB0_5603
	s_branch .LBB0_5604

; __device__ __forceinline__ void st8bf(bf16_t* p, f32x4 a, f32x4 b) { *(u32x4*)p = pack8(a, b); }
;     __device__ __forceinline__ void operator()(const f32x4 (&acc)[2][2][4][2], const Unit& u, int wr, int wc, int fr, int fq) const {
;     ...
;                 if constexpr (MODE == M_FF1) {
; #pragma unroll
;                     for (int m = 0; m < 4; ++m) rstd[m] = rsqrtf(((const float*)(ws + WS_RSS))[u.pm * 256 + ai * 128 + wr * 64 + m * 16 + fr] * (1.f / 2048.f) + EPS);
;                 }
;     ...
;                         } else if constexpr (MODE == M_FF1) {
; #pragma unroll
;                             for (int q = 0; q < 4; ++q) { const float a = fmaxf(v0[q], 0.f) * rstd[m], b = fmaxf(v1[q], 0.f) * rstd[m]; v0[q] = a * a; v1[q] = b * b; }
;                             st8bf((bf16_t*)(ws + WS_HM) + (size_t)r * 8192 + u.pn * 256 + cl, v0, v1);
.LBB0_5619:
	v_mov_b32_e32 v132, v142
	v_mov_b32_e32 v158, v143
	s_lshl_b32 s6, s6, 8
	s_add_i32 s6, s6, s55
	v_add_u32_e32 v132, s6, v132
	v_ashrrev_i32_e32 v133, 31, v132
	v_lshl_add_u64 v[134:135], v[132:133], 2, s[18:19]
	flat_load_dword v159, v[134:135]
	v_add_u32_e32 v150, 16, v132
	v_add_u32_e32 v136, 32, v132
	v_ashrrev_i32_e32 v151, 31, v150
	v_ashrrev_i32_e32 v137, 31, v136
	v_add_u32_e32 v134, 48, v132
	v_lshl_add_u64 v[152:153], v[150:151], 2, s[18:19]
	v_lshl_add_u64 v[154:155], v[136:137], 2, s[18:19]
	v_ashrrev_i32_e32 v135, 31, v134
	v_lshl_add_u64 v[156:157], v[134:135], 2, s[18:19]
	flat_load_dword v152, v[152:153]
	s_nop 0
	flat_load_dword v153, v[154:155]
	s_nop 0
	flat_load_dword v154, v[156:157]
	v_add_u32_e32 v210, 0x80, v132
	v_ashrrev_i32_e32 v211, 31, v210
	v_lshl_add_u64 v[212:213], v[210:211], 2, s[18:19]
	flat_load_dword v220, v[212:213]
	v_add_u32_e32 v210, 0x90, v132
	v_ashrrev_i32_e32 v211, 31, v210
	v_lshl_add_u64 v[214:215], v[210:211], 2, s[18:19]
	flat_load_dword v221, v[214:215]
	v_add_u32_e32 v210, 0xa0, v132
	v_ashrrev_i32_e32 v211, 31, v210
	v_lshl_add_u64 v[216:217], v[210:211], 2, s[18:19]
	flat_load_dword v222, v[216:217]
	v_add_u32_e32 v210, 0xb0, v132
	v_ashrrev_i32_e32 v211, 31, v210
	v_lshl_add_u64 v[218:219], v[210:211], 2, s[18:19]
	flat_load_dword v223, v[218:219]
	s_lshl_b32 s6, s7, 8
	s_ashr_i32 s7, s6, 31
	v_max_f32_e32 v120, v120, v120
	s_lshl_b64 s[6:7], s[6:7], 1
	v_max_f32_e32 v121, v121, v121
	v_max_f32_e32 v122, v122, v122
	v_max_f32_e32 v123, v123, v123
	v_max_f32_e32 v155, 0, v120
	v_lshl_add_u32 v120, v158, 3, s56
	s_add_u32 s34, s66, s6
	v_max_f32_e32 v156, 0, v121
	v_max_f32_e32 v160, 0, v122
	v_max_f32_e32 v162, 0, v123
	v_ashrrev_i32_e32 v121, 31, v120
	s_addc_u32 s35, s67, s7
	v_lshlrev_b64 v[122:123], 14, v[132:133]
	v_max_f32_e32 v126, v126, v126
	v_max_f32_e32 v127, v127, v127
	v_lshlrev_b64 v[120:121], 1, v[120:121]
	v_lshl_add_u64 v[122:123], s[34:35], 0, v[122:123]
	v_max_f32_e32 v157, 0, v126
	v_max_f32_e32 v161, 0, v127
	v_lshl_add_u64 v[126:127], v[122:123], 0, v[120:121]
	v_max_f32_e32 v124, v124, v124
	v_max_f32_e32 v125, v125, v125
	v_max_f32_e32 v124, 0, v124
	v_max_f32_e32 v125, 0, v125
	v_max_f32_e32 v112, v112, v112
	v_max_f32_e32 v113, v113, v113
	v_max_f32_e32 v114, v114, v114
	v_max_f32_e32 v112, 0, v112
	v_max_f32_e32 v113, 0, v113
	v_max_f32_e32 v114, 0, v114
	v_max_f32_e32 v115, v115, v115
	v_max_f32_e32 v116, v116, v116
	v_max_f32_e32 v115, 0, v115
	v_max_f32_e32 v116, 0, v116
	v_max_f32_e32 v104, v104, v104
	v_max_f32_e32 v104, 0, v104
	v_max_f32_e32 v105, v105, v105
	v_max_f32_e32 v106, v106, v106
	v_max_f32_e32 v105, 0, v105
	v_max_f32_e32 v106, 0, v106
	v_max_f32_e32 v108, v108, v108
	v_max_f32_e32 v107, v107, v107
	v_max_f32_e32 v108, 0, v108
	v_max_f32_e32 v107, 0, v107
	v_max_f32_e32 v96, v96, v96
	v_max_f32_e32 v97, v97, v97
	v_max_f32_e32 v98, v98, v98
	v_max_f32_e32 v96, 0, v96
	v_max_f32_e32 v97, 0, v97
	v_max_f32_e32 v98, 0, v98
	v_max_f32_e32 v99, v99, v99
	v_max_f32_e32 v100, v100, v100
	v_max_f32_e32 v99, 0, v99
	v_max_f32_e32 v100, 0, v100
	v_max_f32_e32 v88, v88, v88
	v_max_f32_e32 v88, 0, v88
	v_max_f32_e32 v89, v89, v89
	v_max_f32_e32 v90, v90, v90
	v_max_f32_e32 v89, 0, v89
	v_max_f32_e32 v90, 0, v90
	v_max_f32_e32 v92, v92, v92
	v_max_f32_e32 v91, v91, v91
	v_max_f32_e32 v92, 0, v92
	v_max_f32_e32 v91, 0, v91
	v_max_f32_e32 v80, v80, v80
	v_max_f32_e32 v81, v81, v81
	s_waitcnt vmcnt(0) lgkmcnt(0)
	v_fmamk_f32 v122, v159, 0x3a000000, v149
	v_mul_f32_e32 v123, 0x4b800000, v122
	v_cmp_gt_f32_e32 vcc, s68, v122
	v_max_f32_e32 v82, v82, v82
	v_max_f32_e32 v80, 0, v80
	v_cndmask_b32_e32 v122, v122, v123, vcc
	v_rsq_f32_e32 v122, v122
	v_max_f32_e32 v81, 0, v81
	v_fmamk_f32 v133, v152, 0x3a000000, v149
	v_fmamk_f32 v152, v153, 0x3a000000, v149
	v_mul_f32_e32 v123, 0x4b800000, v133
	v_cmp_gt_f32_e64 s[6:7], s68, v133
	v_fmamk_f32 v153, v154, 0x3a000000, v149
	v_mul_f32_e32 v154, 0x4b800000, v152
	v_cndmask_b32_e64 v123, v133, v123, s[6:7]
	v_cmp_gt_f32_e64 s[8:9], s68, v152
	v_mul_f32_e32 v158, 0x4b800000, v153
	v_cmp_gt_f32_e64 s[10:11], s68, v153
	v_cndmask_b32_e64 v133, v152, v154, s[8:9]
	v_rsq_f32_e32 v123, v123
	v_cndmask_b32_e64 v152, v153, v158, s[10:11]
	v_rsq_f32_e32 v133, v133
	v_rsq_f32_e32 v152, v152
	v_mul_f32_e32 v153, 0x45800000, v122
	v_cndmask_b32_e32 v153, v122, v153, vcc
	v_mul_f32_e32 v122, 0x45800000, v123
	v_mul_f32_e32 v154, 0x45800000, v133
	v_cndmask_b32_e64 v159, v123, v122, s[6:7]
	v_mul_f32_e32 v122, v124, v153
	v_mul_f32_e32 v158, 0x45800000, v152
	v_cndmask_b32_e64 v133, v133, v154, s[8:9]
	v_mul_f32_e32 v123, v155, v153
	v_mul_f32_e32 v124, v125, v153
	v_mul_f32_e32 v125, v156, v153
	v_mul_f32_e32 v154, v157, v153
	v_mul_f32_e32 v122, v122, v122
	v_cndmask_b32_e64 v152, v152, v158, s[10:11]
	v_mul_f32_e32 v155, v160, v153
	v_mul_f32_e32 v156, v161, v153
	v_mul_f32_e32 v157, v162, v153
	v_mul_f32_e32 v158, v123, v123
	v_mul_f32_e32 v123, v124, v124
	v_mul_f32_e32 v124, v125, v125
	v_mul_f32_e32 v125, v154, v154
	v_cvt_pk_bf16_f32 v122, v122, v123
	v_mul_f32_e32 v112, v112, v153
	v_mul_f32_e32 v113, v113, v153
	v_mul_f32_e32 v114, v114, v153
	v_mul_f32_e32 v154, v155, v155
	v_mul_f32_e32 v155, v156, v156
	v_mul_f32_e32 v156, v157, v157
	v_cvt_pk_bf16_f32 v123, v125, v155
	v_cvt_pk_bf16_f32 v124, v158, v124
	v_cvt_pk_bf16_f32 v125, v154, v156
	flat_store_dwordx4 v[126:127], v[122:125]
	v_mul_f32_e32 v115, v115, v153
	v_mul_f32_e32 v116, v116, v153
	v_mul_f32_e32 v122, v112, v112
	v_max_f32_e32 v112, v117, v117
	v_mul_f32_e32 v117, v113, v113
	v_max_f32_e32 v113, v118, v118
	v_mul_f32_e32 v118, v114, v114
; __device__ __forceinline__ void st8bf(bf16_t* p, f32x4 a, f32x4 b) { *(u32x4*)p = pack8(a, b); }
;     __device__ __forceinline__ void operator()(const f32x4 (&acc)[2][2][4][2], const Unit& u, int wr, int wc, int fr, int fq) const {
;     ...
;                         } else if constexpr (MODE == M_FF1) {
; #pragma unroll
;                             for (int q = 0; q < 4; ++q) { const float a = fmaxf(v0[q], 0.f) * rstd[m], b = fmaxf(v1[q], 0.f) * rstd[m]; v0[q] = a * a; v1[q] = b * b; }
;                             st8bf((bf16_t*)(ws + WS_HM) + (size_t)r * 8192 + u.pn * 256 + cl, v0, v1);
	v_max_f32_e32 v114, v119, v119
	v_max_f32_e32 v112, 0, v112
	v_max_f32_e32 v113, 0, v113
	v_max_f32_e32 v114, 0, v114
	v_mul_f32_e32 v112, v112, v153
	v_mul_f32_e32 v113, v113, v153
	v_mul_f32_e32 v114, v114, v153
	v_mul_f32_e32 v112, v112, v112
	v_mul_f32_e32 v113, v113, v113
	v_mul_f32_e32 v114, v114, v114
	v_mul_f32_e32 v115, v115, v115
	v_mul_f32_e32 v116, v116, v116
	v_cvt_pk_bf16_f32 v112, v116, v112
	v_cvt_pk_bf16_f32 v113, v113, v114
	v_cvt_pk_bf16_f32 v114, v122, v117
	v_cvt_pk_bf16_f32 v115, v118, v115
	v_mul_f32_e32 v104, v104, v159
	flat_store_dwordx4 v[126:127], v[112:115] offset:256
	v_mul_f32_e32 v105, v105, v159
	v_mul_f32_e32 v106, v106, v159
	v_mul_f32_e32 v115, v104, v104
	v_max_f32_e32 v104, v109, v109
	v_max_f32_e32 v104, 0, v104
	v_mul_f32_e32 v116, v105, v105
	v_max_f32_e32 v105, v110, v110
	v_mul_f32_e32 v110, v106, v106
	v_max_f32_e32 v106, v111, v111
	v_lshlrev_b64 v[112:113], 14, v[150:151]
	v_mul_f32_e32 v104, v104, v159
	v_max_f32_e32 v105, 0, v105
	v_max_f32_e32 v106, 0, v106
	v_lshl_add_u64 v[112:113], s[34:35], 0, v[112:113]
	v_mul_f32_e32 v108, v108, v159
	v_mul_f32_e32 v104, v104, v104
	v_mul_f32_e32 v105, v105, v159
	v_mul_f32_e32 v106, v106, v159
	v_mul_f32_e32 v107, v107, v159
	v_mul_f32_e32 v114, v108, v108
	v_mul_f32_e32 v105, v105, v105
	v_mul_f32_e32 v106, v106, v106
	v_mul_f32_e32 v107, v107, v107
	v_lshl_add_u64 v[108:109], v[112:113], 0, v[120:121]
	v_cvt_pk_bf16_f32 v104, v114, v104
	v_mul_f32_e32 v96, v96, v159
	v_mul_f32_e32 v97, v97, v159
	v_mul_f32_e32 v98, v98, v159
	v_cvt_pk_bf16_f32 v105, v105, v106
	v_cvt_pk_bf16_f32 v106, v115, v116
	v_cvt_pk_bf16_f32 v107, v110, v107
	flat_store_dwordx4 v[108:109], v[104:107]
	v_mul_f32_e32 v99, v99, v159
	v_mul_f32_e32 v100, v100, v159
	v_mul_f32_e32 v104, v96, v96
	v_max_f32_e32 v96, v101, v101
	v_mul_f32_e32 v101, v97, v97
	v_max_f32_e32 v97, v102, v102
	v_mul_f32_e32 v102, v98, v98
	v_max_f32_e32 v98, v103, v103
	v_max_f32_e32 v96, 0, v96
	v_max_f32_e32 v97, 0, v97
	v_max_f32_e32 v98, 0, v98
	v_mul_f32_e32 v96, v96, v159
	v_mul_f32_e32 v97, v97, v159
	v_mul_f32_e32 v98, v98, v159
	v_mul_f32_e32 v96, v96, v96
	v_mul_f32_e32 v97, v97, v97
	v_mul_f32_e32 v98, v98, v98
	v_mul_f32_e32 v99, v99, v99
	v_mul_f32_e32 v100, v100, v100
	v_cvt_pk_bf16_f32 v96, v100, v96
	v_cvt_pk_bf16_f32 v97, v97, v98
	v_cvt_pk_bf16_f32 v98, v104, v101
	v_cvt_pk_bf16_f32 v99, v102, v99
	v_mul_f32_e32 v88, v88, v133
	flat_store_dwordx4 v[108:109], v[96:99] offset:256
	v_mul_f32_e32 v89, v89, v133
	v_mul_f32_e32 v90, v90, v133
	v_mul_f32_e32 v99, v88, v88
	v_max_f32_e32 v88, v93, v93
	v_max_f32_e32 v88, 0, v88
	v_mul_f32_e32 v100, v89, v89
	v_max_f32_e32 v89, v94, v94
	v_mul_f32_e32 v94, v90, v90
	v_max_f32_e32 v90, v95, v95
	v_lshlrev_b64 v[96:97], 14, v[136:137]
	v_mul_f32_e32 v88, v88, v133
	v_max_f32_e32 v89, 0, v89
	v_max_f32_e32 v90, 0, v90
	v_lshl_add_u64 v[96:97], s[34:35], 0, v[96:97]
	v_mul_f32_e32 v92, v92, v133
	v_mul_f32_e32 v88, v88, v88
	v_mul_f32_e32 v89, v89, v133
	v_mul_f32_e32 v90, v90, v133
	v_mul_f32_e32 v91, v91, v133
	v_max_f32_e32 v82, 0, v82
	v_mul_f32_e32 v98, v92, v92
	v_mul_f32_e32 v89, v89, v89
	v_mul_f32_e32 v90, v90, v90
	v_mul_f32_e32 v91, v91, v91
	v_lshl_add_u64 v[92:93], v[96:97], 0, v[120:121]
	v_cvt_pk_bf16_f32 v88, v98, v88
	v_mul_f32_e32 v80, v80, v133
	v_mul_f32_e32 v81, v81, v133
	v_mul_f32_e32 v82, v82, v133
	v_cvt_pk_bf16_f32 v89, v89, v90
	v_cvt_pk_bf16_f32 v90, v99, v100
	v_cvt_pk_bf16_f32 v91, v94, v91
	flat_store_dwordx4 v[92:93], v[88:91]
	v_max_f32_e32 v83, v83, v83
	v_max_f32_e32 v84, v84, v84
	v_mul_f32_e32 v88, v80, v80
	v_max_f32_e32 v80, v85, v85
	v_mul_f32_e32 v85, v81, v81
	v_max_f32_e32 v81, v86, v86
	v_mul_f32_e32 v86, v82, v82
	v_max_f32_e32 v82, v87, v87
	v_max_f32_e32 v80, 0, v80
	v_max_f32_e32 v81, 0, v81
	v_max_f32_e32 v82, 0, v82
	v_max_f32_e32 v83, 0, v83
	v_max_f32_e32 v84, 0, v84
	v_mul_f32_e32 v80, v80, v133
	v_mul_f32_e32 v81, v81, v133
	v_mul_f32_e32 v82, v82, v133
	v_mul_f32_e32 v83, v83, v133
	v_max_f32_e32 v72, v72, v72
	v_mul_f32_e32 v84, v84, v133
	v_mul_f32_e32 v80, v80, v80
	v_mul_f32_e32 v81, v81, v81
	v_mul_f32_e32 v82, v82, v82
	v_mul_f32_e32 v83, v83, v83
	v_max_f32_e32 v72, 0, v72
	v_max_f32_e32 v73, v73, v73
	v_max_f32_e32 v74, v74, v74
	v_mul_f32_e32 v84, v84, v84
	v_cvt_pk_bf16_f32 v80, v84, v80
	v_cvt_pk_bf16_f32 v81, v81, v82
	v_cvt_pk_bf16_f32 v82, v88, v85
	v_cvt_pk_bf16_f32 v83, v86, v83
	v_mul_f32_e32 v72, v72, v152
	v_max_f32_e32 v73, 0, v73
	v_max_f32_e32 v74, 0, v74
	flat_store_dwordx4 v[92:93], v[80:83] offset:256
	v_mul_f32_e32 v73, v73, v152
	v_mul_f32_e32 v74, v74, v152
	v_mul_f32_e32 v83, v72, v72
	v_max_f32_e32 v72, v77, v77
	v_max_f32_e32 v76, v76, v76
	v_max_f32_e32 v72, 0, v72
	v_mul_f32_e32 v84, v73, v73
	v_max_f32_e32 v73, v78, v78
	v_mul_f32_e32 v78, v74, v74
	v_max_f32_e32 v74, v79, v79
	v_max_f32_e32 v75, v75, v75
	v_lshlrev_b64 v[80:81], 14, v[134:135]
	v_max_f32_e32 v76, 0, v76
	v_mul_f32_e32 v72, v72, v152
	v_max_f32_e32 v73, 0, v73
	v_max_f32_e32 v74, 0, v74
	v_max_f32_e32 v75, 0, v75
	v_max_f32_e32 v64, v64, v64
	v_max_f32_e32 v65, v65, v65
	v_max_f32_e32 v66, v66, v66
	v_lshl_add_u64 v[80:81], s[34:35], 0, v[80:81]
	v_mul_f32_e32 v76, v76, v152
	v_mul_f32_e32 v72, v72, v72
	v_mul_f32_e32 v73, v73, v152
	v_mul_f32_e32 v74, v74, v152
	v_mul_f32_e32 v75, v75, v152
	v_max_f32_e32 v64, 0, v64
	v_max_f32_e32 v65, 0, v65
	v_max_f32_e32 v66, 0, v66
	v_mul_f32_e32 v82, v76, v76
	v_mul_f32_e32 v73, v73, v73
	v_mul_f32_e32 v74, v74, v74
	v_mul_f32_e32 v75, v75, v75
	v_lshl_add_u64 v[76:77], v[80:81], 0, v[120:121]
	v_cvt_pk_bf16_f32 v72, v82, v72
	v_mul_f32_e32 v64, v64, v152
; __device__ __forceinline__ void st8bf(bf16_t* p, f32x4 a, f32x4 b) { *(u32x4*)p = pack8(a, b); }
;     __device__ __forceinline__ void operator()(const f32x4 (&acc)[2][2][4][2], const Unit& u, int wr, int wc, int fr, int fq) const {
;     ...
;                 if constexpr (MODE == M_FF1) {
; #pragma unroll
;                     for (int m = 0; m < 4; ++m) rstd[m] = rsqrtf(((const float*)(ws + WS_RSS))[u.pm * 256 + ai * 128 + wr * 64 + m * 16 + fr] * (1.f / 2048.f) + EPS);
;                 }
;     ...
;                         } else if constexpr (MODE == M_FF1) {
; #pragma unroll
;                             for (int q = 0; q < 4; ++q) { const float a = fmaxf(v0[q], 0.f) * rstd[m], b = fmaxf(v1[q], 0.f) * rstd[m]; v0[q] = a * a; v1[q] = b * b; }
;                             st8bf((bf16_t*)(ws + WS_HM) + (size_t)r * 8192 + u.pn * 256 + cl, v0, v1);
	v_mul_f32_e32 v65, v65, v152
	v_mul_f32_e32 v66, v66, v152
	v_cvt_pk_bf16_f32 v73, v73, v74
	v_cvt_pk_bf16_f32 v74, v83, v84
	v_cvt_pk_bf16_f32 v75, v78, v75
	flat_store_dwordx4 v[76:77], v[72:75]
	v_max_f32_e32 v68, v68, v68
	v_max_f32_e32 v67, v67, v67
	v_mul_f32_e32 v72, v64, v64
	v_max_f32_e32 v64, v69, v69
	v_mul_f32_e32 v69, v65, v65
	v_max_f32_e32 v65, v70, v70
	v_mul_f32_e32 v70, v66, v66
	v_max_f32_e32 v66, v71, v71
	v_max_f32_e32 v64, 0, v64
	v_max_f32_e32 v65, 0, v65
	v_max_f32_e32 v66, 0, v66
	v_max_f32_e32 v68, 0, v68
	v_mul_f32_e32 v64, v64, v152
	v_mul_f32_e32 v65, v65, v152
	v_mul_f32_e32 v66, v66, v152
	v_max_f32_e32 v67, 0, v67
	v_mul_f32_e32 v68, v68, v152
	v_mul_f32_e32 v64, v64, v64
	v_mul_f32_e32 v65, v65, v65
	v_mul_f32_e32 v67, v67, v152
	v_mul_f32_e32 v66, v66, v66
	v_mul_f32_e32 v68, v68, v68
	v_mul_f32_e32 v67, v67, v67
	v_cvt_pk_bf16_f32 v64, v68, v64
	v_cvt_pk_bf16_f32 v65, v65, v66
	v_cvt_pk_bf16_f32 v66, v72, v69
	v_cvt_pk_bf16_f32 v67, v70, v67
	flat_store_dwordx4 v[76:77], v[64:67] offset:256
	v_add_u32_e32 v68, 0x90, v132
	v_ashrrev_i32_e32 v69, 31, v68
	v_add_u32_e32 v66, 0x80, v132
	v_ashrrev_i32_e32 v67, 31, v66
	v_lshl_add_u64 v[64:65], v[66:67], 2, s[18:19]
	v_mov_b32_e32 v74, v220
	v_add_u32_e32 v70, 0xa0, v132
	v_lshl_add_u64 v[64:65], v[68:69], 2, s[18:19]
	v_ashrrev_i32_e32 v71, 31, v70
	v_mov_b32_e32 v75, v221
	v_lshl_add_u64 v[64:65], v[70:71], 2, s[18:19]
	v_mov_b32_e32 v76, v222
	v_add_u32_e32 v64, 0xb0, v132
	v_ashrrev_i32_e32 v65, 31, v64
	v_lshl_add_u64 v[72:73], v[64:65], 2, s[18:19]
	v_mov_b32_e32 v72, v223
	v_max_f32_e32 v56, v56, v56
	v_max_f32_e32 v56, 0, v56
	v_max_f32_e32 v57, v57, v57
	v_max_f32_e32 v58, v58, v58
	v_max_f32_e32 v57, 0, v57
	v_max_f32_e32 v58, 0, v58
	v_max_f32_e32 v60, v60, v60
	v_max_f32_e32 v59, v59, v59
	v_lshlrev_b64 v[66:67], 14, v[66:67]
	v_max_f32_e32 v60, 0, v60
	v_max_f32_e32 v59, 0, v59
	v_max_f32_e32 v48, v48, v48
	v_max_f32_e32 v49, v49, v49
	v_max_f32_e32 v50, v50, v50
	v_lshl_add_u64 v[66:67], s[34:35], 0, v[66:67]
	v_max_f32_e32 v48, 0, v48
	v_max_f32_e32 v49, 0, v49
	v_max_f32_e32 v50, 0, v50
	v_max_f32_e32 v51, v51, v51
	v_max_f32_e32 v52, v52, v52
	v_max_f32_e32 v51, 0, v51
	v_max_f32_e32 v52, 0, v52
	v_max_f32_e32 v40, v40, v40
	v_max_f32_e32 v40, 0, v40
	v_max_f32_e32 v41, v41, v41
	v_max_f32_e32 v42, v42, v42
	v_max_f32_e32 v41, 0, v41
	v_max_f32_e32 v42, 0, v42
	v_max_f32_e32 v44, v44, v44
	v_max_f32_e32 v43, v43, v43
	v_max_f32_e32 v44, 0, v44
	v_max_f32_e32 v43, 0, v43
	v_max_f32_e32 v32, v32, v32
	v_max_f32_e32 v33, v33, v33
	v_max_f32_e32 v34, v34, v34
	v_max_f32_e32 v32, 0, v32
	v_max_f32_e32 v33, 0, v33
	v_max_f32_e32 v34, 0, v34
	v_max_f32_e32 v35, v35, v35
	v_max_f32_e32 v36, v36, v36
	v_max_f32_e32 v35, 0, v35
	v_max_f32_e32 v36, 0, v36
	v_max_f32_e32 v24, v24, v24
	v_max_f32_e32 v24, 0, v24
	v_max_f32_e32 v25, v25, v25
	v_max_f32_e32 v26, v26, v26
	v_max_f32_e32 v25, 0, v25
	v_max_f32_e32 v26, 0, v26
	v_max_f32_e32 v28, v28, v28
	v_max_f32_e32 v27, v27, v27
	v_max_f32_e32 v28, 0, v28
	v_max_f32_e32 v27, 0, v27
	v_max_f32_e32 v16, v16, v16
	v_max_f32_e32 v17, v17, v17
	v_max_f32_e32 v18, v18, v18
	v_max_f32_e32 v16, 0, v16
	v_max_f32_e32 v17, 0, v17
	v_max_f32_e32 v18, 0, v18
	v_max_f32_e32 v19, v19, v19
	v_max_f32_e32 v20, v20, v20
	v_max_f32_e32 v19, 0, v19
	v_max_f32_e32 v20, 0, v20
	v_max_f32_e32 v8, v8, v8
	v_max_f32_e32 v8, 0, v8
	v_max_f32_e32 v9, v9, v9
	v_max_f32_e32 v10, v10, v10
	v_max_f32_e32 v9, 0, v9
	v_max_f32_e32 v10, 0, v10
	v_max_f32_e32 v12, v12, v12
	v_fmamk_f32 v73, v74, 0x3a000000, v149
	v_mul_f32_e32 v74, 0x4b800000, v73
	v_cmp_gt_f32_e32 vcc, s68, v73
	v_max_f32_e32 v11, v11, v11
	v_max_f32_e32 v12, 0, v12
	v_cndmask_b32_e32 v73, v73, v74, vcc
	v_rsq_f32_e32 v73, v73
	v_fmamk_f32 v74, v75, 0x3a000000, v149
	v_mul_f32_e32 v75, 0x4b800000, v74
	v_cmp_gt_f32_e64 s[6:7], s68, v74
	v_fmamk_f32 v76, v76, 0x3a000000, v149
	v_mul_f32_e32 v77, 0x4b800000, v76
	v_cndmask_b32_e64 v74, v74, v75, s[6:7]
	v_mul_f32_e32 v75, 0x45800000, v73
	v_cndmask_b32_e32 v73, v73, v75, vcc
	v_cmp_gt_f32_e32 vcc, s68, v76
	v_fmamk_f32 v72, v72, 0x3a000000, v149
	v_rsq_f32_e32 v74, v74
	v_cndmask_b32_e32 v76, v76, v77, vcc
	v_mul_f32_e32 v77, 0x4b800000, v72
	v_cmp_gt_f32_e64 s[8:9], s68, v72
	v_rsq_f32_e32 v76, v76
	v_mul_f32_e32 v56, v56, v73
	v_cndmask_b32_e64 v72, v72, v77, s[8:9]
	v_rsq_f32_e32 v72, v72
	v_mul_f32_e32 v77, v56, v56
	v_max_f32_e32 v56, v61, v61
	v_mul_f32_e32 v57, v57, v73
	v_mul_f32_e32 v58, v58, v73
	v_mul_f32_e32 v75, 0x45800000, v74
	v_max_f32_e32 v56, 0, v56
	v_mul_f32_e32 v78, v57, v57
	v_max_f32_e32 v57, v62, v62
	v_mul_f32_e32 v62, v58, v58
	v_max_f32_e32 v58, v63, v63
	v_cndmask_b32_e64 v74, v74, v75, s[6:7]
	v_mul_f32_e32 v75, 0x45800000, v76
	v_mul_f32_e32 v56, v56, v73
	v_max_f32_e32 v57, 0, v57
	v_max_f32_e32 v58, 0, v58
	v_cndmask_b32_e32 v75, v76, v75, vcc
	v_mul_f32_e32 v76, 0x45800000, v72
	v_mul_f32_e32 v60, v60, v73
	v_mul_f32_e32 v56, v56, v56
	v_mul_f32_e32 v57, v57, v73
	v_mul_f32_e32 v58, v58, v73
	v_mul_f32_e32 v59, v59, v73
	v_cndmask_b32_e64 v72, v72, v76, s[8:9]
	v_mul_f32_e32 v76, v60, v60
	v_mul_f32_e32 v57, v57, v57
	v_mul_f32_e32 v58, v58, v58
	v_mul_f32_e32 v59, v59, v59
	v_lshl_add_u64 v[60:61], v[66:67], 0, v[120:121]
	v_cvt_pk_bf16_f32 v56, v76, v56
	v_mul_f32_e32 v48, v48, v73
	v_mul_f32_e32 v49, v49, v73
	v_mul_f32_e32 v50, v50, v73
	v_cvt_pk_bf16_f32 v57, v57, v58
	v_cvt_pk_bf16_f32 v58, v77, v78
	v_cvt_pk_bf16_f32 v59, v62, v59
	flat_store_dwordx4 v[60:61], v[56:59]
	v_mul_f32_e32 v51, v51, v73
	v_mul_f32_e32 v52, v52, v73
	v_mul_f32_e32 v56, v48, v48
	v_max_f32_e32 v48, v53, v53
; #define PG8_BAR __builtin_amdgcn_s_barrier()
; __device__ __forceinline__ void st8bf(bf16_t* p, f32x4 a, f32x4 b) { *(u32x4*)p = pack8(a, b); }
; template <class Epi, class Sched, bool ALIGN_EPI>
; __device__ __forceinline__ void gemm_phase(LAS unsigned char* lds, const Gemm g, const Sched& S, const Epi& E, int wid) {
;     ...
;         if (!cur.chain) {
;             if constexpr (ALIGN_EPI) { if (wr == 0) PG8_BAR; }
;             E(acc, cur, wr, wc, fr, fq);
;         }
;         if (!has_next) break;
;         if (!cur.chain) {
; #pragma unroll
;             for (int a = 0; a < 2; ++a)
; #pragma unroll
;                 for (int b = 0; b < 2; ++b)
; #pragma unroll
;                     for (int m = 0; m < 4; ++m)
; #pragma unroll
;                         for (int n = 0; n < 2; ++n) acc[a][b][m][n] = (f32x4){0.f, 0.f, 0.f, 0.f};
;             if constexpr (ALIGN_EPI) { if (wr == 1) PG8_BAR; }
;         }
;         cur = nxt; cA = nA; cB = nB; ++ui;
;     __device__ __forceinline__ void operator()(const f32x4 (&acc)[2][2][4][2], const Unit& u, int wr, int wc, int fr, int fq) const {
;     ...
;                         } else if constexpr (MODE == M_FF1) {
; #pragma unroll
;                             for (int q = 0; q < 4; ++q) { const float a = fmaxf(v0[q], 0.f) * rstd[m], b = fmaxf(v1[q], 0.f) * rstd[m]; v0[q] = a * a; v1[q] = b * b; }
;                             st8bf((bf16_t*)(ws + WS_HM) + (size_t)r * 8192 + u.pn * 256 + cl, v0, v1);
	v_mul_f32_e32 v53, v49, v49
	v_max_f32_e32 v49, v54, v54
	v_mul_f32_e32 v54, v50, v50
	v_max_f32_e32 v50, v55, v55
	v_max_f32_e32 v48, 0, v48
	v_max_f32_e32 v49, 0, v49
	v_max_f32_e32 v50, 0, v50
	v_mul_f32_e32 v48, v48, v73
	v_mul_f32_e32 v49, v49, v73
	v_mul_f32_e32 v50, v50, v73
	v_mul_f32_e32 v48, v48, v48
	v_mul_f32_e32 v49, v49, v49
	v_mul_f32_e32 v50, v50, v50
	v_mul_f32_e32 v51, v51, v51
	v_mul_f32_e32 v52, v52, v52
	v_cvt_pk_bf16_f32 v48, v52, v48
	v_cvt_pk_bf16_f32 v49, v49, v50
	v_cvt_pk_bf16_f32 v50, v56, v53
	v_cvt_pk_bf16_f32 v51, v54, v51
	v_mul_f32_e32 v40, v40, v74
	flat_store_dwordx4 v[60:61], v[48:51] offset:256
	v_mul_f32_e32 v41, v41, v74
	v_mul_f32_e32 v42, v42, v74
	v_mul_f32_e32 v51, v40, v40
	v_max_f32_e32 v40, v45, v45
	v_max_f32_e32 v40, 0, v40
	v_mul_f32_e32 v52, v41, v41
	v_max_f32_e32 v41, v46, v46
	v_mul_f32_e32 v46, v42, v42
	v_max_f32_e32 v42, v47, v47
	v_lshlrev_b64 v[48:49], 14, v[68:69]
	v_mul_f32_e32 v40, v40, v74
	v_max_f32_e32 v41, 0, v41
	v_max_f32_e32 v42, 0, v42
	v_lshl_add_u64 v[48:49], s[34:35], 0, v[48:49]
	v_mul_f32_e32 v44, v44, v74
	v_mul_f32_e32 v40, v40, v40
	v_mul_f32_e32 v41, v41, v74
	v_mul_f32_e32 v42, v42, v74
	v_mul_f32_e32 v43, v43, v74
	v_mul_f32_e32 v50, v44, v44
	v_mul_f32_e32 v41, v41, v41
	v_mul_f32_e32 v42, v42, v42
	v_mul_f32_e32 v43, v43, v43
	v_lshl_add_u64 v[44:45], v[48:49], 0, v[120:121]
	v_cvt_pk_bf16_f32 v40, v50, v40
	v_mul_f32_e32 v32, v32, v74
	v_mul_f32_e32 v33, v33, v74
	v_mul_f32_e32 v34, v34, v74
	v_cvt_pk_bf16_f32 v41, v41, v42
	v_cvt_pk_bf16_f32 v42, v51, v52
	v_cvt_pk_bf16_f32 v43, v46, v43
	flat_store_dwordx4 v[44:45], v[40:43]
	v_mul_f32_e32 v35, v35, v74
	v_mul_f32_e32 v36, v36, v74
	v_mul_f32_e32 v40, v32, v32
	v_max_f32_e32 v32, v37, v37
	v_mul_f32_e32 v37, v33, v33
	v_max_f32_e32 v33, v38, v38
	v_mul_f32_e32 v38, v34, v34
	v_max_f32_e32 v34, v39, v39
	v_max_f32_e32 v32, 0, v32
	v_max_f32_e32 v33, 0, v33
	v_max_f32_e32 v34, 0, v34
	v_mul_f32_e32 v32, v32, v74
	v_mul_f32_e32 v33, v33, v74
	v_mul_f32_e32 v34, v34, v74
	v_mul_f32_e32 v32, v32, v32
	v_mul_f32_e32 v33, v33, v33
	v_mul_f32_e32 v34, v34, v34
	v_mul_f32_e32 v35, v35, v35
	v_mul_f32_e32 v36, v36, v36
	v_cvt_pk_bf16_f32 v32, v36, v32
	v_cvt_pk_bf16_f32 v33, v33, v34
	v_cvt_pk_bf16_f32 v34, v40, v37
	v_cvt_pk_bf16_f32 v35, v38, v35
	v_mul_f32_e32 v24, v24, v75
	flat_store_dwordx4 v[44:45], v[32:35] offset:256
	v_mul_f32_e32 v25, v25, v75
	v_mul_f32_e32 v26, v26, v75
	v_mul_f32_e32 v35, v24, v24
	v_max_f32_e32 v24, v29, v29
	v_max_f32_e32 v24, 0, v24
	v_mul_f32_e32 v36, v25, v25
	v_max_f32_e32 v25, v30, v30
	v_mul_f32_e32 v30, v26, v26
	v_max_f32_e32 v26, v31, v31
	v_lshlrev_b64 v[32:33], 14, v[70:71]
	v_mul_f32_e32 v24, v24, v75
	v_max_f32_e32 v25, 0, v25
	v_max_f32_e32 v26, 0, v26
	v_lshl_add_u64 v[32:33], s[34:35], 0, v[32:33]
	v_mul_f32_e32 v28, v28, v75
	v_mul_f32_e32 v24, v24, v24
	v_mul_f32_e32 v25, v25, v75
	v_mul_f32_e32 v26, v26, v75
	v_mul_f32_e32 v27, v27, v75
	v_mul_f32_e32 v34, v28, v28
	v_mul_f32_e32 v25, v25, v25
	v_mul_f32_e32 v26, v26, v26
	v_mul_f32_e32 v27, v27, v27
	v_lshl_add_u64 v[28:29], v[32:33], 0, v[120:121]
	v_cvt_pk_bf16_f32 v24, v34, v24
	v_mul_f32_e32 v16, v16, v75
	v_mul_f32_e32 v17, v17, v75
	v_mul_f32_e32 v18, v18, v75
	v_cvt_pk_bf16_f32 v25, v25, v26
	v_cvt_pk_bf16_f32 v26, v35, v36
	v_cvt_pk_bf16_f32 v27, v30, v27
	flat_store_dwordx4 v[28:29], v[24:27]
	v_mul_f32_e32 v19, v19, v75
	v_mul_f32_e32 v20, v20, v75
	v_mul_f32_e32 v24, v16, v16
	v_max_f32_e32 v16, v21, v21
	v_mul_f32_e32 v21, v17, v17
	v_max_f32_e32 v17, v22, v22
	v_mul_f32_e32 v22, v18, v18
	v_max_f32_e32 v18, v23, v23
	v_max_f32_e32 v16, 0, v16
	v_max_f32_e32 v17, 0, v17
	v_max_f32_e32 v18, 0, v18
	v_mul_f32_e32 v16, v16, v75
	v_mul_f32_e32 v17, v17, v75
	v_mul_f32_e32 v18, v18, v75
	v_mul_f32_e32 v16, v16, v16
	v_mul_f32_e32 v17, v17, v17
	v_mul_f32_e32 v18, v18, v18
	v_mul_f32_e32 v19, v19, v19
	v_mul_f32_e32 v20, v20, v20
	v_cvt_pk_bf16_f32 v16, v20, v16
	v_cvt_pk_bf16_f32 v17, v17, v18
	v_cvt_pk_bf16_f32 v18, v24, v21
	v_cvt_pk_bf16_f32 v19, v22, v19
	v_mul_f32_e32 v8, v8, v72
	flat_store_dwordx4 v[28:29], v[16:19] offset:256
	v_mul_f32_e32 v9, v9, v72
	v_mul_f32_e32 v10, v10, v72
	v_mul_f32_e32 v19, v8, v8
	v_max_f32_e32 v8, v13, v13
	v_max_f32_e32 v8, 0, v8
	v_mul_f32_e32 v20, v9, v9
	v_max_f32_e32 v9, v14, v14
	v_mul_f32_e32 v14, v10, v10
	v_max_f32_e32 v10, v15, v15
	v_lshlrev_b64 v[16:17], 14, v[64:65]
	v_mul_f32_e32 v8, v8, v72
	v_max_f32_e32 v9, 0, v9
	v_max_f32_e32 v10, 0, v10
	v_max_f32_e32 v11, 0, v11
	v_max_f32_e32 v0, v0, v0
	v_max_f32_e32 v1, v1, v1
	v_max_f32_e32 v2, v2, v2
	v_lshl_add_u64 v[16:17], s[34:35], 0, v[16:17]
	v_mul_f32_e32 v12, v12, v72
	v_mul_f32_e32 v8, v8, v8
	v_mul_f32_e32 v9, v9, v72
	v_mul_f32_e32 v10, v10, v72
	v_mul_f32_e32 v11, v11, v72
	v_max_f32_e32 v0, 0, v0
	v_max_f32_e32 v1, 0, v1
	v_max_f32_e32 v2, 0, v2
	v_mul_f32_e32 v18, v12, v12
	v_mul_f32_e32 v9, v9, v9
	v_mul_f32_e32 v10, v10, v10
	v_mul_f32_e32 v11, v11, v11
	v_lshl_add_u64 v[12:13], v[16:17], 0, v[120:121]
	v_cvt_pk_bf16_f32 v8, v18, v8
	v_mul_f32_e32 v0, v0, v72
	v_mul_f32_e32 v1, v1, v72
	v_mul_f32_e32 v2, v2, v72
	v_cvt_pk_bf16_f32 v9, v9, v10
	v_cvt_pk_bf16_f32 v10, v19, v20
	v_cvt_pk_bf16_f32 v11, v14, v11
	flat_store_dwordx4 v[12:13], v[8:11]
	v_max_f32_e32 v3, v3, v3
	v_max_f32_e32 v4, v4, v4
	v_mul_f32_e32 v8, v0, v0
	v_max_f32_e32 v0, v5, v5
	v_mul_f32_e32 v5, v1, v1
	v_max_f32_e32 v1, v6, v6
	v_mul_f32_e32 v6, v2, v2
	v_max_f32_e32 v2, v7, v7
	v_max_f32_e32 v0, 0, v0
	v_max_f32_e32 v1, 0, v1
	v_max_f32_e32 v2, 0, v2
	v_max_f32_e32 v3, 0, v3
	v_max_f32_e32 v4, 0, v4
	v_mul_f32_e32 v0, v0, v72
	v_mul_f32_e32 v1, v1, v72
	v_mul_f32_e32 v2, v2, v72
	v_mul_f32_e32 v3, v3, v72
	v_mul_f32_e32 v4, v4, v72
	v_mul_f32_e32 v0, v0, v0
	v_mul_f32_e32 v1, v1, v1
	v_mul_f32_e32 v2, v2, v2
	v_mul_f32_e32 v3, v3, v3
	s_andn2_b64 vcc, exec, s[4:5]
	s_mov_b64 s[4:5], -1
	v_mul_f32_e32 v4, v4, v4
	v_cvt_pk_bf16_f32 v0, v4, v0
	v_cvt_pk_bf16_f32 v1, v1, v2
	v_cvt_pk_bf16_f32 v2, v8, v5
	v_cvt_pk_bf16_f32 v3, v6, v3
	flat_store_dwordx4 v[12:13], v[0:3] offset:256
	s_cbranch_vccnz .LBB0_5608
	s_andn2_b64 vcc, exec, s[14:15]
	s_cbranch_vccnz .LBB0_5607
	s_barrier
	s_branch .LBB0_5607

; #define LAS __attribute__((address_space(3)))
; __device__ __forceinline__ unsigned xb_ld(unsigned* p)              { return __hip_atomic_load(p, RLX_AGENT); }
; __device__ __forceinline__ unsigned xb_add(unsigned* p, unsigned v) { return __hip_atomic_fetch_add(p, v, RLX_AGENT); }
; __device__ __forceinline__ unsigned xb_xcc_id() { return (unsigned)__builtin_amdgcn_s_getreg((3 << 11) | 20) & 0xFu; }
; #define PHASE_END } ++ph; if (ph > ph_lo && ph < ph_hi) { grid_bar((unsigned*)ws, bst, (unsigned)G, wave); }
; __device__ __forceinline__ void grid_bar(unsigned* bar, volatile LAS unsigned* st, unsigned G, int wave) {
;     asm volatile("s_waitcnt vmcnt(0) lgkmcnt(0)" ::: "memory");
;     __syncthreads();
;     int l; asm volatile("v_mbcnt_lo_u32_b32 %0, -1, 0\n\tv_mbcnt_hi_u32_b32 %0, -1, %0" : "=v"(l));
;     if (wave == 0 && l == 0) {
;         const unsigned x = xb_xcc_id();
;         __builtin_amdgcn_s_waitcnt(0);
;         unsigned nloc = st[0], nx = st[1];
;         if (nloc == 0u) { xcd_barrier_complete(bar, x, G, nloc, nx); st[0] = nloc; st[1] = nx; }
;         const unsigned old = xb_add(&bar[XB_XSUB(x)], 1u);
;         const unsigned gen = old / nloc;
;         if (old + 1u == (gen + 1u) * nloc) {
;             __builtin_amdgcn_fence(__ATOMIC_RELEASE, "agent");
;             asm volatile("s_waitcnt vmcnt(0)" ::: "memory");
;             const unsigned og = xb_add(&bar[XB_TOP], 1u);
;             const unsigned tg = og / nx;
;             if (og + 1u == (tg + 1u) * nx) xb_add(&bar[XB_TOPGEN], 1u);
;             else XB_SPIN(xb_ld(&bar[XB_TOPGEN]) == tg, bar);
;             __builtin_amdgcn_fence(__ATOMIC_ACQUIRE, "agent");
;             xb_add(&bar[XB_XGEN(x)], 1u);
;             asm volatile("s_waitcnt vmcnt(0)" ::: "memory");
;         } else {
;             XB_SPIN(xb_ld(&bar[XB_XGEN(x)]) == gen, bar);
;             __builtin_amdgcn_fence(__ATOMIC_ACQUIRE, "agent");
;             asm volatile("s_waitcnt vmcnt(0)" ::: "memory");
;         }
;     }
;     __syncthreads();
; }
; __global__ void __launch_bounds__(512, 2) hybrid_fwd(Args A0) {
;     ...
;     PHASE_BEGIN(15)
;         const Gemm g{(const bf16_t*)(ws + WS_HM), (const bf16_t*)(ws + WS_WF2), DFF, DFF, DFF};
;         pg8::StaticOrder S; S.init(T, DM, DFF, DFF, G, bid, 4); Epi<M_FF2> E{&A, 0};
;         pg8::gemm_phase<Epi<M_FF2>, pg8::StaticOrder, true>(lds, g, S, E, wave);
;     PHASE_END
; }
.LBB0_5702:
.LBB0_5756:
	s_endpgm

; __global__ void __launch_bounds__(512, 2) hybrid_fwd(Args A0) {
	.amdhsa_kernel _Z10hybrid_fwd4Args
		.amdhsa_group_segment_fixed_size 0
		.amdhsa_private_segment_fixed_size 0
		.amdhsa_kernarg_size 408
		.amdhsa_user_sgpr_count 2
		.amdhsa_user_sgpr_dispatch_ptr 0
		.amdhsa_user_sgpr_queue_ptr 0
		.amdhsa_user_sgpr_kernarg_segment_ptr 1
		.amdhsa_user_sgpr_dispatch_id 0
		.amdhsa_user_sgpr_kernarg_preload_length 0
		.amdhsa_user_sgpr_kernarg_preload_offset 0
		.amdhsa_user_sgpr_private_segment_size 0
		.amdhsa_uses_dynamic_stack 0
		.amdhsa_enable_private_segment 0
		.amdhsa_system_sgpr_workgroup_id_x 1
		.amdhsa_system_sgpr_workgroup_id_y 0
		.amdhsa_system_sgpr_workgroup_id_z 0
		.amdhsa_system_sgpr_workgroup_info 0
		.amdhsa_system_vgpr_workitem_id 2
		.amdhsa_next_free_vgpr 256
		.amdhsa_next_free_sgpr 102
		.amdhsa_accum_offset 256
		.amdhsa_reserve_vcc 1
		.amdhsa_float_round_mode_32 0
		.amdhsa_float_round_mode_16_64 0
		.amdhsa_float_denorm_mode_32 3
		.amdhsa_float_denorm_mode_16_64 3
		.amdhsa_dx10_clamp 1
		.amdhsa_ieee_mode 1
		.amdhsa_fp16_overflow 0
		.amdhsa_tg_split 0
		.amdhsa_exception_fp_ieee_invalid_op 0
		.amdhsa_exception_fp_denorm_src 0
		.amdhsa_exception_fp_ieee_div_zero 0
		.amdhsa_exception_fp_ieee_overflow 0
		.amdhsa_exception_fp_ieee_underflow 0
		.amdhsa_exception_fp_ieee_inexact 0
		.amdhsa_exception_int_div_zero 0
	.end_amdhsa_kernel

; __global__ void __launch_bounds__(512, 2) hybrid_fwd(Args A0) {
amdhsa.kernels:
  - .agpr_count:     0
    .args:
      - .offset:         0
        .size:           152
        .value_kind:     by_value
      - .offset:         152
        .size:           4
        .value_kind:     hidden_block_count_x
      - .offset:         156
        .size:           4
        .value_kind:     hidden_block_count_y
      - .offset:         160
        .size:           4
        .value_kind:     hidden_block_count_z
      - .offset:         164
        .size:           2
        .value_kind:     hidden_group_size_x
      - .offset:         166
        .size:           2
        .value_kind:     hidden_group_size_y
      - .offset:         168
        .size:           2
        .value_kind:     hidden_group_size_z
      - .offset:         170
        .size:           2
        .value_kind:     hidden_remainder_x
      - .offset:         172
        .size:           2
        .value_kind:     hidden_remainder_y
      - .offset:         174
        .size:           2
        .value_kind:     hidden_remainder_z
      - .offset:         192
        .size:           8
        .value_kind:     hidden_global_offset_x
      - .offset:         200
        .size:           8
        .value_kind:     hidden_global_offset_y
      - .offset:         208
        .size:           8
        .value_kind:     hidden_global_offset_z
      - .offset:         216
        .size:           2
        .value_kind:     hidden_grid_dims
      - .offset:         240
        .size:           8
        .value_kind:     hidden_multigrid_sync_arg
      - .offset:         272
        .size:           4
        .value_kind:     hidden_dynamic_lds_size
    .group_segment_fixed_size: 0
    .kernarg_segment_align: 8
    .kernarg_segment_size: 408
    .language:       OpenCL C
    .language_version:
      - 2
      - 0
    .max_flat_workgroup_size: 512
    .name:           _Z10hybrid_fwd4Args
    .private_segment_fixed_size: 0
    .sgpr_count:     108
    .sgpr_spill_count: 18
    .symbol:         _Z10hybrid_fwd4Args.kd
    .uniform_work_group_size: 1
    .uses_dynamic_stack: false
    .vgpr_count:     256
    .vgpr_spill_count: 0
    .wavefront_size: 64
